# skip entry grid.sync body (census barrier after prologue does not need it)
# baseline (speedup 1.0000x reference)
.LBB0_6:
	s_or_b64 exec, exec, s[4:5]
	v_lshrrev_b32_e32 v1, 20, v0
	v_lshrrev_b32_e32 v0, 10, v0
	v_or_b32_e32 v0, v0, v1
	s_movk_i32 s4, 0x3ff
	v_and_or_b32 v0, v0, s4, v218
	v_cmp_eq_u32_e32 vcc, 0, v0
	s_barrier
	s_and_saveexec_b64 s[4:5], vcc
	s_branch .LBB0_16
	buffer_wbl2 sc1
	s_waitcnt vmcnt(0)
	s_load_dwordx2 s[6:7], s[6:7], 0x58
	v_mov_b32_e32 v2, 0
	s_mov_b64 s[8:9], exec
	v_mbcnt_lo_u32_b32 v1, s8, 0
	v_mbcnt_hi_u32_b32 v1, s9, v1
	s_waitcnt lgkmcnt(0)
	global_load_dword v0, v2, s[6:7] offset:40
	v_cmp_eq_u32_e32 vcc, 0, v1
	s_and_saveexec_b64 s[10:11], vcc
	s_cbranch_execz .LBB0_9
	s_bcnt1_i32_b64 s8, s[8:9]
	v_mov_b32_e32 v3, s8
	global_atomic_add v3, v2, v3, s[6:7] offset:32 sc0
